# grid barrier: one workgroup per XCD starts an L2 write-back from an idle wave as soon as it arrives
# speedup vs baseline: 1.0383x; 1.0006x over previous
; __device__ __forceinline__ void xcd_barrier(const XcdBarrier& b) {
;     asm volatile("s_waitcnt vmcnt(0)" ::: "memory");
;     __syncthreads();
.LBB0_2003:
	s_or_b64 exec, exec, s[0:1]
	s_lshr_b32 s4, s76, 3
	s_cmp_lg_u32 s4, 0
	s_cbranch_scc1 .Lwb_skip
	s_cmp_lg_u32 s90, 64
	s_cbranch_scc1 .Lwb_skip
	buffer_wbl2 sc1
.Lwb_skip:
	s_mov_b64 s[0:1], 0
	s_waitcnt lgkmcnt(0)
	s_barrier
